# GLU epilogue: drain (vmcnt(0)) then prefetch the z rows two blocks ahead into three rotating register sets; no counted waits
# baseline (speedup 1.0000x reference)
; __device__ __forceinline__ unsigned cvt_pk_bf16(float lo, float hi) { const f32x2 v = {lo, hi}; return __builtin_bit_cast(unsigned, __builtin_convertvector(v, bf16x2_t)); }
; __device__ __forceinline__ float bf_lo(unsigned w) { return __uint_as_float(w << 16); }
; __device__ __forceinline__ float bf_hi(unsigned w) { return __uint_as_float(w & 0xffff0000u); }
; __device__ __forceinline__ float fast_sigmoid(float v) { return __builtin_amdgcn_rcpf(1.0f + __builtin_amdgcn_exp2f(-1.4426950408889634f * v)); }
; #define ssq2 ((float*)(WSPTR() + WS_SSQ2))
;     __device__ __forceinline__ void operator()(const f32x4 (&acc)[2][2][4][2], const Unit& u, int wr, int wc, int fr, int fq) const {
;         const int row0 = u.pm * BM + wr * 64 + fr;
; #pragma unroll
;         for (int ai = 0; ai < 2; ++ai)
; #pragma unroll
;             for (int m = 0; m < 4; ++m) {
;                 const int row = row0 + ai * HALF + m * 16;
;                 float ss = 0.f;
; #pragma unroll
;                 for (int bj = 0; bj < 2; ++bj) {
;                     const int c0 = u.pn * BM + bj * HALF + wc * 32 + 8 * fq;
;                     const u32x4 zw = *(const u32x4*)(z + (size_t)row * 512 + c0);
;                     const f32x4 b0 = *(const f32x4*)(bglu + c0), b1 = *(const f32x4*)(bglu + c0 + 4);
;                     const f32x4 a0 = acc[ai][bj][m][0] + b0, a1 = acc[ai][bj][m][1] + b1;
;                     float o[8];
;                     o[0] = bf_lo(zw.x) * fast_sigmoid(a0[0]); o[1] = bf_hi(zw.x) * fast_sigmoid(a0[1]);
;                     o[2] = bf_lo(zw.y) * fast_sigmoid(a0[2]); o[3] = bf_hi(zw.y) * fast_sigmoid(a0[3]);
;                     o[4] = bf_lo(zw.z) * fast_sigmoid(a1[0]); o[5] = bf_hi(zw.z) * fast_sigmoid(a1[1]);
;                     o[6] = bf_lo(zw.w) * fast_sigmoid(a1[2]); o[7] = bf_hi(zw.w) * fast_sigmoid(a1[3]);
; #pragma unroll
;                     for (int j = 0; j < 8; ++j) ss += o[j] * o[j];
;                     u32x4 w; w.x = cvt_pk_bf16(o[0], o[1]); w.y = cvt_pk_bf16(o[2], o[3]); w.z = cvt_pk_bf16(o[4], o[5]); w.w = cvt_pk_bf16(o[6], o[7]);
;                     *(u32x4*)(s + (size_t)row * 1024 + 512 + c0) = w;
;                 }
;                 ss += __shfl_xor(ss, 16); ss += __shfl_xor(ss, 32); if (fq == 0) ssq2[((size_t)u.pn * 32768 + row) * 4 + wc] = ss;
.LBB0_590:
	v_lshl_or_b32 v142, s92, 8, v148
	v_ashrrev_i32_e32 v143, 31, v142
	v_lshl_add_u64 v[140:141], v[142:143], 2, s[80:81]
	v_lshl_add_u32 v144, s19, 8, v146
	v_ashrrev_i32_e32 v145, 31, v144
	v_lshlrev_b64 v[158:159], 10, v[144:145]
	v_lshlrev_b64 v[142:143], 1, v[142:143]
	v_lshl_add_u64 v[158:159], s[76:77], 0, v[158:159]
	v_lshl_add_u64 v[178:179], v[158:159], 0, v[142:143]
	v_mov_b64_e32 v[226:227], v[178:179]
	global_load_dwordx4 v[184:187], v[140:141], off
	global_load_dwordx4 v[188:191], v[140:141], off offset:16
	global_load_dwordx4 v[192:195], v[140:141], off offset:512
	global_load_dwordx4 v[196:199], v[140:141], off offset:528
	global_load_dwordx4 v[200:203], v[226:227], off
	global_load_dwordx4 v[204:207], v[226:227], off offset:256
	s_mov_b32 s100, 0x4000
	s_mov_b32 s101, 0
	v_lshl_add_u64 v[228:229], v[226:227], 0, s[100:101]
	global_load_dwordx4 v[210:213], v[228:229], off
	global_load_dwordx4 v[214:217], v[228:229], off offset:256
	s_nop 1
	s_waitcnt vmcnt(0)
	s_mov_b32 s100, 0x8000
	s_mov_b32 s101, 0
	v_lshl_add_u64 v[228:229], v[226:227], 0, s[100:101]
	global_load_dwordx4 v[230:233], v[228:229], off
	global_load_dwordx4 v[234:237], v[228:229], off offset:256
	s_nop 1
	v_lshlrev_b64 v[180:181], 11, v[144:145]
	v_lshl_add_u64 v[180:181], s[78:79], 0, v[180:181]
	v_lshl_add_u64 v[180:181], v[180:181], 0, v[142:143]
	s_ashr_i32 s93, s92, 31
	s_lshl_b64 s[92:93], s[92:93], 19
	v_mov_b32_e32 v150, v184
	v_mov_b32_e32 v151, v185
	v_mov_b32_e32 v152, v186
	v_mov_b32_e32 v153, v187
	v_mov_b32_e32 v154, v188
	v_mov_b32_e32 v155, v189
	v_mov_b32_e32 v156, v190
	v_mov_b32_e32 v157, v191
	v_mov_b32_e32 v158, v200
	v_mov_b32_e32 v159, v201
	v_mov_b32_e32 v160, v202
	v_mov_b32_e32 v161, v203
	v_pk_add_f32 v[128:129], v[128:129], v[152:153]
	v_pk_add_f32 v[126:127], v[126:127], v[150:151]
	v_pk_add_f32 v[124:125], v[124:125], v[156:157]
	v_pk_add_f32 v[122:123], v[122:123], v[154:155]
	v_mul_f32_e32 v126, 0xbfb8aa3b, v126
	v_mul_f32_e32 v127, 0xbfb8aa3b, v127
	v_mul_f32_e32 v128, 0xbfb8aa3b, v128
	v_mul_f32_e32 v129, 0xbfb8aa3b, v129
	v_mul_f32_e32 v150, 0xbfb8aa3b, v122
	v_mul_f32_e32 v151, 0xbfb8aa3b, v123
	v_mul_f32_e32 v152, 0xbfb8aa3b, v124
	v_mul_f32_e32 v153, 0xbfb8aa3b, v125
	v_exp_f32_e32 v154, v126
	v_exp_f32_e32 v155, v127
	v_exp_f32_e32 v156, v128
	v_exp_f32_e32 v157, v129
	v_exp_f32_e32 v150, v150
	v_exp_f32_e32 v151, v151
	v_exp_f32_e32 v152, v152
	v_exp_f32_e32 v153, v153
	v_lshlrev_b32_e32 v122, 16, v158
	v_and_b32_e32 v123, 0xffff0000, v158
	v_lshlrev_b32_e32 v124, 16, v159
	v_and_b32_e32 v125, 0xffff0000, v159
	v_lshlrev_b32_e32 v126, 16, v160
	v_and_b32_e32 v127, 0xffff0000, v160
	v_lshlrev_b32_e32 v128, 16, v161
	v_and_b32_e32 v129, 0xffff0000, v161
	v_add_f32_e32 v154, 1.0, v154
	v_add_f32_e32 v155, 1.0, v155
	v_add_f32_e32 v156, 1.0, v156
	v_add_f32_e32 v157, 1.0, v157
	v_add_f32_e32 v158, 1.0, v150
	v_add_f32_e32 v159, 1.0, v151
	v_add_f32_e32 v160, 1.0, v152
	v_add_f32_e32 v161, 1.0, v153
	v_rcp_f32_e32 v150, v154
	v_rcp_f32_e32 v151, v155
	v_rcp_f32_e32 v152, v156
	v_rcp_f32_e32 v153, v157
	v_rcp_f32_e32 v154, v158
	v_rcp_f32_e32 v155, v159
	v_rcp_f32_e32 v156, v160
	v_rcp_f32_e32 v157, v161
	v_pk_mul_f32 v[158:159], v[150:151], v[122:123]
	v_pk_mul_f32 v[160:161], v[152:153], v[124:125]
	v_pk_mul_f32 v[182:183], v[154:155], v[126:127]
	v_pk_mul_f32 v[128:129], v[156:157], v[128:129]
	v_cvt_pk_bf16_f32 v122, v158, v159
	v_cvt_pk_bf16_f32 v123, v160, v161
	v_cvt_pk_bf16_f32 v124, v182, v183
	v_cvt_pk_bf16_f32 v125, v128, v129
	global_store_dwordx4 v[180:181], v[122:125], off offset:1024
	s_nop 0
	v_and_b32_e32 v123, 64, v218
	v_xor_b32_e32 v122, 16, v218
	v_add_u32_e32 v123, 64, v123
	v_pk_mul_f32 v[158:159], v[158:159], v[158:159]
	v_xor_b32_e32 v178, 32, v218
	v_cmp_lt_i32_e32 vcc, v122, v123
	v_pk_mul_f32 v[160:161], v[160:161], v[160:161]
	v_add_f32_e32 v158, v158, v159
	v_cndmask_b32_e32 v122, v218, v122, vcc
	v_cmp_lt_i32_e32 vcc, v178, v123
	v_add_f32_e32 v158, v160, v158
	v_add_f32_e32 v158, v161, v158
	v_cndmask_b32_e32 v123, v218, v178, vcc
	v_pk_mul_f32 v[178:179], v[182:183], v[182:183]
	v_pk_mul_f32 v[128:129], v[128:129], v[128:129]
	v_add_f32_e32 v158, v178, v158
	v_add_f32_e32 v158, v179, v158
	v_add_f32_e32 v128, v128, v158
	v_add_f32_e32 v128, v129, v128
	v_lshlrev_b32_e32 v122, 2, v122
	v_mov_b32_e32 v124, v192
	v_mov_b32_e32 v125, v193
	v_mov_b32_e32 v126, v194
	v_mov_b32_e32 v127, v195
	v_mov_b32_e32 v150, v196
	v_mov_b32_e32 v151, v197
	v_mov_b32_e32 v152, v198
	v_mov_b32_e32 v153, v199
	v_mov_b32_e32 v154, v204
	v_mov_b32_e32 v155, v205
	v_mov_b32_e32 v156, v206
	v_mov_b32_e32 v157, v207
	v_pk_add_f32 v[118:119], v[118:119], v[124:125]
	v_pk_add_f32 v[120:121], v[120:121], v[126:127]
	v_pk_add_f32 v[114:115], v[114:115], v[150:151]
	v_mul_f32_e32 v118, 0xbfb8aa3b, v118
	v_mul_f32_e32 v119, 0xbfb8aa3b, v119
	v_pk_add_f32 v[116:117], v[116:117], v[152:153]
	v_mul_f32_e32 v120, 0xbfb8aa3b, v120
	v_mul_f32_e32 v121, 0xbfb8aa3b, v121
	v_mul_f32_e32 v114, 0xbfb8aa3b, v114
	v_mul_f32_e32 v115, 0xbfb8aa3b, v115
	v_exp_f32_e32 v118, v118
	v_exp_f32_e32 v119, v119
	v_mul_f32_e32 v116, 0xbfb8aa3b, v116
	v_mul_f32_e32 v117, 0xbfb8aa3b, v117
	v_exp_f32_e32 v120, v120
	v_exp_f32_e32 v121, v121
	v_exp_f32_e32 v114, v114
	v_exp_f32_e32 v115, v115
	v_exp_f32_e32 v116, v116
	v_exp_f32_e32 v117, v117
	v_add_f32_e32 v118, 1.0, v118
	v_add_f32_e32 v119, 1.0, v119
	v_lshlrev_b32_e32 v124, 16, v154
	v_and_b32_e32 v125, 0xffff0000, v154
	v_lshlrev_b32_e32 v126, 16, v155
	v_and_b32_e32 v127, 0xffff0000, v155
	v_add_f32_e32 v120, 1.0, v120
	v_add_f32_e32 v121, 1.0, v121
	v_add_f32_e32 v154, 1.0, v114
	v_add_f32_e32 v155, 1.0, v115
	v_rcp_f32_e32 v114, v118
	v_rcp_f32_e32 v115, v119
	v_lshlrev_b32_e32 v150, 16, v156
	v_and_b32_e32 v151, 0xffff0000, v156
	v_lshlrev_b32_e32 v152, 16, v157
	v_and_b32_e32 v153, 0xffff0000, v157
	v_add_f32_e32 v156, 1.0, v116
	v_add_f32_e32 v157, 1.0, v117
	v_rcp_f32_e32 v116, v120
	v_rcp_f32_e32 v117, v121
	v_rcp_f32_e32 v118, v154
	v_rcp_f32_e32 v119, v155
	v_pk_mul_f32 v[114:115], v[114:115], v[124:125]
	v_rcp_f32_e32 v120, v156
	v_rcp_f32_e32 v121, v157
	v_pk_mul_f32 v[124:125], v[116:117], v[126:127]
	v_pk_mul_f32 v[116:117], v[114:115], v[114:115]
	v_pk_mul_f32 v[126:127], v[118:119], v[150:151]
	v_add_f32_e32 v116, v116, v128
	v_pk_mul_f32 v[118:119], v[124:125], v[124:125]
	v_add_f32_e32 v116, v117, v116
	v_add_f32_e32 v116, v118, v116
	v_pk_mul_f32 v[150:151], v[120:121], v[152:153]
	v_pk_mul_f32 v[120:121], v[126:127], v[126:127]
	v_add_f32_e32 v116, v119, v116
	v_add_f32_e32 v116, v120, v116
	v_pk_mul_f32 v[152:153], v[150:151], v[150:151]
	v_add_f32_e32 v116, v121, v116
	v_add_f32_e32 v116, v152, v116
	v_add_f32_e32 v117, v153, v116
	ds_bpermute_b32 v119, v122, v117
	v_lshlrev_b32_e32 v116, 2, v123
	v_cvt_pk_bf16_f32 v118, v114, v115
	v_cvt_pk_bf16_f32 v120, v126, v127
	v_cvt_pk_bf16_f32 v121, v150, v151
	s_waitcnt lgkmcnt(0)
; __device__ __forceinline__ unsigned cvt_pk_bf16(float lo, float hi) { const f32x2 v = {lo, hi}; return __builtin_bit_cast(unsigned, __builtin_convertvector(v, bf16x2_t)); }
; __device__ __forceinline__ float bf_lo(unsigned w) { return __uint_as_float(w << 16); }
; __device__ __forceinline__ float bf_hi(unsigned w) { return __uint_as_float(w & 0xffff0000u); }
; __device__ __forceinline__ float fast_sigmoid(float v) { return __builtin_amdgcn_rcpf(1.0f + __builtin_amdgcn_exp2f(-1.4426950408889634f * v)); }
; #define ssq2 ((float*)(WSPTR() + WS_SSQ2))
;     __device__ __forceinline__ void operator()(const f32x4 (&acc)[2][2][4][2], const Unit& u, int wr, int wc, int fr, int fq) const {
;     ...
;                 const int row = row0 + ai * HALF + m * 16;
;                 float ss = 0.f;
; #pragma unroll
;                 for (int bj = 0; bj < 2; ++bj) {
;                     const int c0 = u.pn * BM + bj * HALF + wc * 32 + 8 * fq;
;                     const u32x4 zw = *(const u32x4*)(z + (size_t)row * 512 + c0);
;                     const f32x4 b0 = *(const f32x4*)(bglu + c0), b1 = *(const f32x4*)(bglu + c0 + 4);
;                     const f32x4 a0 = acc[ai][bj][m][0] + b0, a1 = acc[ai][bj][m][1] + b1;
;                     float o[8];
;                     o[0] = bf_lo(zw.x) * fast_sigmoid(a0[0]); o[1] = bf_hi(zw.x) * fast_sigmoid(a0[1]);
;                     o[2] = bf_lo(zw.y) * fast_sigmoid(a0[2]); o[3] = bf_hi(zw.y) * fast_sigmoid(a0[3]);
;                     o[4] = bf_lo(zw.z) * fast_sigmoid(a1[0]); o[5] = bf_hi(zw.z) * fast_sigmoid(a1[1]);
;                     o[6] = bf_lo(zw.w) * fast_sigmoid(a1[2]); o[7] = bf_hi(zw.w) * fast_sigmoid(a1[3]);
; #pragma unroll
;                     for (int j = 0; j < 8; ++j) ss += o[j] * o[j];
;                     u32x4 w; w.x = cvt_pk_bf16(o[0], o[1]); w.y = cvt_pk_bf16(o[2], o[3]); w.z = cvt_pk_bf16(o[4], o[5]); w.w = cvt_pk_bf16(o[6], o[7]);
;                     *(u32x4*)(s + (size_t)row * 1024 + 512 + c0) = w;
;                 }
;                 ss += __shfl_xor(ss, 16); ss += __shfl_xor(ss, 32); if (fq == 0) ssq2[((size_t)u.pn * 32768 + row) * 4 + wc] = ss;
	v_add_f32_e32 v114, v117, v119
	ds_bpermute_b32 v115, v116, v114
	v_cvt_pk_bf16_f32 v119, v124, v125
	global_store_dwordx4 v[180:181], v[118:121], off offset:1280
	s_and_saveexec_b64 s[22:23], s[4:5]
	s_cbranch_execz .LBB0_592
	s_add_u32 s26, s36, s92
	s_addc_u32 s27, s37, s93
	v_lshl_add_u64 v[118:119], v[144:145], 4, s[26:27]
	s_lshl_b32 s52, s38, 2
	v_lshl_add_u64 v[118:119], v[118:119], 0, s[52:53]
	s_waitcnt lgkmcnt(0)
	v_add_f32_e32 v114, v114, v115
	global_store_dword v[118:119], v114, off
.LBB0_592:
	s_or_b64 exec, exec, s[22:23]
	s_waitcnt vmcnt(0)
	s_mov_b32 s100, 0xc000
	s_mov_b32 s101, 0
	v_lshl_add_u64 v[228:229], v[226:227], 0, s[100:101]
	global_load_dwordx4 v[200:203], v[228:229], off
	global_load_dwordx4 v[204:207], v[228:229], off offset:256
	s_nop 1
	v_or_b32_e32 v114, 16, v144
	s_waitcnt lgkmcnt(0)
	v_ashrrev_i32_e32 v115, 31, v114
	v_lshlrev_b64 v[128:129], 10, v[114:115]
	v_lshl_add_u64 v[128:129], s[76:77], 0, v[128:129]
	v_lshl_add_u64 v[128:129], v[128:129], 0, v[142:143]
	v_lshlrev_b64 v[154:155], 11, v[114:115]
	v_lshl_add_u64 v[154:155], s[78:79], 0, v[154:155]
	v_lshl_add_u64 v[154:155], v[154:155], 0, v[142:143]
	v_mov_b32_e32 v118, v184
	v_mov_b32_e32 v119, v185
	v_mov_b32_e32 v120, v186
	v_mov_b32_e32 v121, v187
	v_mov_b32_e32 v124, v188
	v_mov_b32_e32 v125, v189
	v_mov_b32_e32 v126, v190
	v_mov_b32_e32 v127, v191
	v_mov_b32_e32 v150, v210
	v_mov_b32_e32 v151, v211
	v_mov_b32_e32 v152, v212
	v_mov_b32_e32 v153, v213
	v_pk_add_f32 v[112:113], v[112:113], v[120:121]
	v_pk_add_f32 v[110:111], v[110:111], v[118:119]
	v_pk_add_f32 v[108:109], v[108:109], v[126:127]
	v_pk_add_f32 v[106:107], v[106:107], v[124:125]
	v_mul_f32_e32 v110, 0xbfb8aa3b, v110
	v_mul_f32_e32 v111, 0xbfb8aa3b, v111
	v_mul_f32_e32 v112, 0xbfb8aa3b, v112
	v_mul_f32_e32 v113, 0xbfb8aa3b, v113
	v_mul_f32_e32 v106, 0xbfb8aa3b, v106
	v_mul_f32_e32 v107, 0xbfb8aa3b, v107
	v_mul_f32_e32 v108, 0xbfb8aa3b, v108
	v_mul_f32_e32 v109, 0xbfb8aa3b, v109
	v_exp_f32_e32 v117, v110
	v_exp_f32_e32 v118, v111
	v_exp_f32_e32 v119, v112
	v_exp_f32_e32 v120, v113
	v_exp_f32_e32 v121, v106
	v_exp_f32_e32 v123, v107
	v_exp_f32_e32 v124, v108
	v_exp_f32_e32 v125, v109
	v_lshlrev_b32_e32 v106, 16, v150
	v_and_b32_e32 v107, 0xffff0000, v150
	v_lshlrev_b32_e32 v108, 16, v151
	v_and_b32_e32 v109, 0xffff0000, v151
	v_lshlrev_b32_e32 v110, 16, v152
	v_and_b32_e32 v111, 0xffff0000, v152
	v_add_f32_e32 v117, 1.0, v117
	v_add_f32_e32 v126, 1.0, v118
	v_add_f32_e32 v127, 1.0, v119
	v_add_f32_e32 v145, 1.0, v120
	v_add_f32_e32 v150, 1.0, v121
	v_add_f32_e32 v123, 1.0, v123
	v_add_f32_e32 v151, 1.0, v124
	v_add_f32_e32 v152, 1.0, v125
	v_rcp_f32_e32 v118, v117
	v_rcp_f32_e32 v119, v126
	v_rcp_f32_e32 v120, v127
	v_rcp_f32_e32 v121, v145
	v_rcp_f32_e32 v124, v150
	v_rcp_f32_e32 v125, v123
	v_rcp_f32_e32 v126, v151
	v_rcp_f32_e32 v127, v152
	v_lshlrev_b32_e32 v112, 16, v153
	v_and_b32_e32 v113, 0xffff0000, v153
	v_pk_mul_f32 v[150:151], v[118:119], v[106:107]
	v_pk_mul_f32 v[152:153], v[120:121], v[108:109]
	v_pk_mul_f32 v[124:125], v[124:125], v[110:111]
	v_pk_mul_f32 v[126:127], v[126:127], v[112:113]
	v_cvt_pk_bf16_f32 v106, v150, v151
	v_cvt_pk_bf16_f32 v107, v152, v153
	v_cvt_pk_bf16_f32 v108, v124, v125
	v_cvt_pk_bf16_f32 v109, v126, v127
	global_store_dwordx4 v[154:155], v[106:109], off offset:1024
	s_nop 0
	v_pk_mul_f32 v[128:129], v[150:151], v[150:151]
	v_pk_mul_f32 v[150:151], v[152:153], v[152:153]
	v_add_f32_e32 v117, v128, v129
	v_add_f32_e32 v117, v150, v117
	v_pk_mul_f32 v[124:125], v[124:125], v[124:125]
	v_add_f32_e32 v117, v151, v117
	v_add_f32_e32 v117, v124, v117
	v_pk_mul_f32 v[126:127], v[126:127], v[126:127]
	v_add_f32_e32 v117, v125, v117
	v_add_f32_e32 v117, v126, v117
	v_add_f32_e32 v117, v127, v117
	v_mov_b32_e32 v106, v192
	v_mov_b32_e32 v107, v193
	v_mov_b32_e32 v108, v194
	v_mov_b32_e32 v109, v195
	v_mov_b32_e32 v110, v196
	v_mov_b32_e32 v111, v197
	v_mov_b32_e32 v112, v198
	v_mov_b32_e32 v113, v199
	v_mov_b32_e32 v118, v214
	v_mov_b32_e32 v119, v215
	v_mov_b32_e32 v120, v216
	v_mov_b32_e32 v121, v217
	v_pk_add_f32 v[102:103], v[102:103], v[106:107]
	v_pk_add_f32 v[104:105], v[104:105], v[108:109]
	v_pk_add_f32 v[98:99], v[98:99], v[110:111]
	v_mul_f32_e32 v102, 0xbfb8aa3b, v102
	v_mul_f32_e32 v103, 0xbfb8aa3b, v103
	v_pk_add_f32 v[100:101], v[100:101], v[112:113]
	v_mul_f32_e32 v104, 0xbfb8aa3b, v104
	v_mul_f32_e32 v105, 0xbfb8aa3b, v105
	v_mul_f32_e32 v98, 0xbfb8aa3b, v98
	v_mul_f32_e32 v99, 0xbfb8aa3b, v99
	v_exp_f32_e32 v102, v102
	v_exp_f32_e32 v103, v103
	v_mul_f32_e32 v100, 0xbfb8aa3b, v100
	v_mul_f32_e32 v101, 0xbfb8aa3b, v101
	v_exp_f32_e32 v104, v104
	v_exp_f32_e32 v105, v105
	v_exp_f32_e32 v98, v98
	v_exp_f32_e32 v99, v99
	v_exp_f32_e32 v100, v100
	v_exp_f32_e32 v101, v101
	v_add_f32_e32 v102, 1.0, v102
	v_add_f32_e32 v103, 1.0, v103
	v_lshlrev_b32_e32 v106, 16, v118
	v_and_b32_e32 v107, 0xffff0000, v118
	v_lshlrev_b32_e32 v108, 16, v119
	v_and_b32_e32 v109, 0xffff0000, v119
	v_add_f32_e32 v104, 1.0, v104
	v_add_f32_e32 v105, 1.0, v105
	v_add_f32_e32 v118, 1.0, v98
	v_add_f32_e32 v119, 1.0, v99
	v_rcp_f32_e32 v98, v102
	v_rcp_f32_e32 v99, v103
	v_lshlrev_b32_e32 v110, 16, v120
	v_and_b32_e32 v111, 0xffff0000, v120
	v_lshlrev_b32_e32 v112, 16, v121
	v_and_b32_e32 v113, 0xffff0000, v121
	v_add_f32_e32 v120, 1.0, v100
	v_add_f32_e32 v121, 1.0, v101
	v_rcp_f32_e32 v100, v104
	v_rcp_f32_e32 v101, v105
	v_rcp_f32_e32 v102, v118
	v_rcp_f32_e32 v103, v119
	v_pk_mul_f32 v[98:99], v[98:99], v[106:107]
	v_pk_mul_f32 v[106:107], v[100:101], v[108:109]
	v_pk_mul_f32 v[100:101], v[98:99], v[98:99]
	v_rcp_f32_e32 v104, v120
	v_rcp_f32_e32 v105, v121
	v_add_f32_e32 v100, v100, v117
	v_pk_mul_f32 v[108:109], v[106:107], v[106:107]
	v_add_f32_e32 v100, v101, v100
	v_pk_mul_f32 v[102:103], v[102:103], v[110:111]
	v_add_f32_e32 v100, v108, v100
	v_pk_mul_f32 v[110:111], v[102:103], v[102:103]
	v_add_f32_e32 v100, v109, v100
	v_pk_mul_f32 v[104:105], v[104:105], v[112:113]
	v_add_f32_e32 v100, v110, v100
	v_pk_mul_f32 v[112:113], v[104:105], v[104:105]
	v_add_f32_e32 v100, v111, v100
	v_add_f32_e32 v100, v112, v100
	v_add_f32_e32 v101, v113, v100
	ds_bpermute_b32 v108, v122, v101
	v_cvt_pk_bf16_f32 v100, v98, v99
	v_cvt_pk_bf16_f32 v102, v102, v103
	v_cvt_pk_bf16_f32 v103, v104, v105
	s_waitcnt lgkmcnt(0)
	v_add_f32_e32 v98, v101, v108
	ds_bpermute_b32 v99, v116, v98
	v_cvt_pk_bf16_f32 v101, v106, v107
	global_store_dwordx4 v[154:155], v[100:103], off offset:1280
	s_and_saveexec_b64 s[22:23], s[4:5]
	s_cbranch_execz .LBB0_594
	s_add_u32 s26, s36, s92
	s_addc_u32 s27, s37, s93
	v_lshl_add_u64 v[100:101], v[114:115], 4, s[26:27]
	s_lshl_b32 s52, s38, 2
	v_lshl_add_u64 v[100:101], v[100:101], 0, s[52:53]
	s_waitcnt lgkmcnt(0)
	v_add_f32_e32 v98, v98, v99
	global_store_dword v[100:101], v98, off
; __device__ __forceinline__ unsigned cvt_pk_bf16(float lo, float hi) { const f32x2 v = {lo, hi}; return __builtin_bit_cast(unsigned, __builtin_convertvector(v, bf16x2_t)); }
; __device__ __forceinline__ float bf_lo(unsigned w) { return __uint_as_float(w << 16); }
; __device__ __forceinline__ float bf_hi(unsigned w) { return __uint_as_float(w & 0xffff0000u); }
; __device__ __forceinline__ float fast_sigmoid(float v) { return __builtin_amdgcn_rcpf(1.0f + __builtin_amdgcn_exp2f(-1.4426950408889634f * v)); }
; #define ssq2 ((float*)(WSPTR() + WS_SSQ2))
;     __device__ __forceinline__ void operator()(const f32x4 (&acc)[2][2][4][2], const Unit& u, int wr, int wc, int fr, int fq) const {
;     ...
;                 const int row = row0 + ai * HALF + m * 16;
;                 float ss = 0.f;
; #pragma unroll
;                 for (int bj = 0; bj < 2; ++bj) {
;                     const int c0 = u.pn * BM + bj * HALF + wc * 32 + 8 * fq;
;                     const u32x4 zw = *(const u32x4*)(z + (size_t)row * 512 + c0);
;                     const f32x4 b0 = *(const f32x4*)(bglu + c0), b1 = *(const f32x4*)(bglu + c0 + 4);
;                     const f32x4 a0 = acc[ai][bj][m][0] + b0, a1 = acc[ai][bj][m][1] + b1;
;                     float o[8];
;                     o[0] = bf_lo(zw.x) * fast_sigmoid(a0[0]); o[1] = bf_hi(zw.x) * fast_sigmoid(a0[1]);
;                     o[2] = bf_lo(zw.y) * fast_sigmoid(a0[2]); o[3] = bf_hi(zw.y) * fast_sigmoid(a0[3]);
;                     o[4] = bf_lo(zw.z) * fast_sigmoid(a1[0]); o[5] = bf_hi(zw.z) * fast_sigmoid(a1[1]);
;                     o[6] = bf_lo(zw.w) * fast_sigmoid(a1[2]); o[7] = bf_hi(zw.w) * fast_sigmoid(a1[3]);
; #pragma unroll
;                     for (int j = 0; j < 8; ++j) ss += o[j] * o[j];
;                     u32x4 w; w.x = cvt_pk_bf16(o[0], o[1]); w.y = cvt_pk_bf16(o[2], o[3]); w.z = cvt_pk_bf16(o[4], o[5]); w.w = cvt_pk_bf16(o[6], o[7]);
;                     *(u32x4*)(s + (size_t)row * 1024 + 512 + c0) = w;
;                 }
;                 ss += __shfl_xor(ss, 16); ss += __shfl_xor(ss, 32); if (fq == 0) ssq2[((size_t)u.pn * 32768 + row) * 4 + wc] = ss;
.LBB0_594:
	s_or_b64 exec, exec, s[22:23]
	s_waitcnt vmcnt(0)
	s_mov_b32 s100, 0x20000
	s_mov_b32 s101, 0
	v_lshl_add_u64 v[228:229], v[226:227], 0, s[100:101]
	global_load_dwordx4 v[210:213], v[228:229], off
	global_load_dwordx4 v[214:217], v[228:229], off offset:256
	s_nop 1
	v_or_b32_e32 v98, 32, v144
	s_waitcnt lgkmcnt(0)
	v_ashrrev_i32_e32 v99, 31, v98
	v_lshlrev_b64 v[108:109], 10, v[98:99]
	v_lshl_add_u64 v[108:109], s[76:77], 0, v[108:109]
	v_lshl_add_u64 v[112:113], v[108:109], 0, v[142:143]
	v_lshlrev_b64 v[114:115], 11, v[98:99]
	v_lshl_add_u64 v[114:115], s[78:79], 0, v[114:115]
	v_lshl_add_u64 v[114:115], v[114:115], 0, v[142:143]
	v_mov_b32_e32 v100, v184
	v_mov_b32_e32 v101, v185
	v_mov_b32_e32 v102, v186
	v_mov_b32_e32 v103, v187
	v_mov_b32_e32 v104, v188
	v_mov_b32_e32 v105, v189
	v_mov_b32_e32 v106, v190
	v_mov_b32_e32 v107, v191
	v_mov_b32_e32 v108, v230
	v_mov_b32_e32 v109, v231
	v_mov_b32_e32 v110, v232
	v_mov_b32_e32 v111, v233
	v_pk_add_f32 v[96:97], v[96:97], v[102:103]
	v_pk_add_f32 v[94:95], v[94:95], v[100:101]
	v_pk_add_f32 v[92:93], v[92:93], v[106:107]
	v_pk_add_f32 v[90:91], v[90:91], v[104:105]
	v_mul_f32_e32 v94, 0xbfb8aa3b, v94
	v_mul_f32_e32 v95, 0xbfb8aa3b, v95
	v_mul_f32_e32 v96, 0xbfb8aa3b, v96
	v_mul_f32_e32 v97, 0xbfb8aa3b, v97
	v_mul_f32_e32 v90, 0xbfb8aa3b, v90
	v_mul_f32_e32 v91, 0xbfb8aa3b, v91
	v_mul_f32_e32 v92, 0xbfb8aa3b, v92
	v_mul_f32_e32 v93, 0xbfb8aa3b, v93
	v_exp_f32_e32 v100, v94
	v_exp_f32_e32 v101, v95
	v_exp_f32_e32 v102, v96
	v_exp_f32_e32 v103, v97
	v_exp_f32_e32 v104, v90
	v_exp_f32_e32 v105, v91
	v_exp_f32_e32 v106, v92
	v_exp_f32_e32 v107, v93
	v_add_f32_e32 v100, 1.0, v100
	v_add_f32_e32 v101, 1.0, v101
	v_add_f32_e32 v102, 1.0, v102
	v_add_f32_e32 v103, 1.0, v103
	v_add_f32_e32 v104, 1.0, v104
	v_add_f32_e32 v105, 1.0, v105
	v_add_f32_e32 v106, 1.0, v106
	v_add_f32_e32 v107, 1.0, v107
	v_rcp_f32_e32 v100, v100
	v_rcp_f32_e32 v101, v101
	v_rcp_f32_e32 v102, v102
	v_rcp_f32_e32 v103, v103
	v_rcp_f32_e32 v104, v104
	v_rcp_f32_e32 v105, v105
	v_rcp_f32_e32 v106, v106
	v_rcp_f32_e32 v107, v107
	v_lshlrev_b32_e32 v90, 16, v108
	v_and_b32_e32 v91, 0xffff0000, v108
	v_lshlrev_b32_e32 v92, 16, v109
	v_and_b32_e32 v93, 0xffff0000, v109
	v_lshlrev_b32_e32 v94, 16, v110
	v_and_b32_e32 v95, 0xffff0000, v110
	v_lshlrev_b32_e32 v96, 16, v111
	v_and_b32_e32 v97, 0xffff0000, v111
	v_pk_mul_f32 v[108:109], v[100:101], v[90:91]
	v_pk_mul_f32 v[110:111], v[102:103], v[92:93]
	v_pk_mul_f32 v[104:105], v[104:105], v[94:95]
	v_pk_mul_f32 v[106:107], v[106:107], v[96:97]
	v_cvt_pk_bf16_f32 v90, v108, v109
	v_cvt_pk_bf16_f32 v91, v110, v111
	v_cvt_pk_bf16_f32 v92, v104, v105
	v_cvt_pk_bf16_f32 v93, v106, v107
	global_store_dwordx4 v[114:115], v[90:93], off offset:1024
	s_nop 0
	v_pk_mul_f32 v[108:109], v[108:109], v[108:109]
	v_pk_mul_f32 v[110:111], v[110:111], v[110:111]
	v_add_f32_e32 v108, v108, v109
	v_add_f32_e32 v108, v110, v108
	v_pk_mul_f32 v[104:105], v[104:105], v[104:105]
	v_add_f32_e32 v108, v111, v108
	v_add_f32_e32 v104, v104, v108
	v_pk_mul_f32 v[106:107], v[106:107], v[106:107]
	v_add_f32_e32 v104, v105, v104
	v_add_f32_e32 v104, v106, v104
	v_mov_b32_e32 v90, v192
	v_mov_b32_e32 v91, v193
	v_mov_b32_e32 v92, v194
	v_mov_b32_e32 v93, v195
	v_mov_b32_e32 v94, v196
	v_mov_b32_e32 v95, v197
	v_mov_b32_e32 v96, v198
	v_mov_b32_e32 v97, v199
	v_mov_b32_e32 v100, v234
	v_mov_b32_e32 v101, v235
	v_mov_b32_e32 v102, v236
	v_mov_b32_e32 v103, v237
	v_pk_add_f32 v[86:87], v[86:87], v[90:91]
	v_pk_add_f32 v[88:89], v[88:89], v[92:93]
	v_pk_add_f32 v[82:83], v[82:83], v[94:95]
	v_mul_f32_e32 v86, 0xbfb8aa3b, v86
	v_mul_f32_e32 v87, 0xbfb8aa3b, v87
	v_pk_add_f32 v[84:85], v[84:85], v[96:97]
	v_mul_f32_e32 v88, 0xbfb8aa3b, v88
	v_mul_f32_e32 v89, 0xbfb8aa3b, v89
	v_mul_f32_e32 v82, 0xbfb8aa3b, v82
	v_mul_f32_e32 v83, 0xbfb8aa3b, v83
	v_exp_f32_e32 v86, v86
	v_exp_f32_e32 v87, v87
	v_mul_f32_e32 v84, 0xbfb8aa3b, v84
	v_mul_f32_e32 v85, 0xbfb8aa3b, v85
	v_exp_f32_e32 v88, v88
	v_exp_f32_e32 v89, v89
	v_exp_f32_e32 v82, v82
	v_exp_f32_e32 v83, v83
	v_exp_f32_e32 v84, v84
	v_exp_f32_e32 v85, v85
	v_add_f32_e32 v86, 1.0, v86
	v_add_f32_e32 v87, 1.0, v87
	v_lshlrev_b32_e32 v90, 16, v100
	v_and_b32_e32 v91, 0xffff0000, v100
	v_lshlrev_b32_e32 v92, 16, v101
	v_and_b32_e32 v93, 0xffff0000, v101
	v_add_f32_e32 v88, 1.0, v88
	v_add_f32_e32 v89, 1.0, v89
	v_add_f32_e32 v100, 1.0, v82
	v_add_f32_e32 v101, 1.0, v83
	v_rcp_f32_e32 v82, v86
	v_rcp_f32_e32 v83, v87
	v_lshlrev_b32_e32 v94, 16, v102
	v_and_b32_e32 v95, 0xffff0000, v102
	v_lshlrev_b32_e32 v96, 16, v103
	v_and_b32_e32 v97, 0xffff0000, v103
	v_add_f32_e32 v102, 1.0, v84
	v_add_f32_e32 v103, 1.0, v85
	v_rcp_f32_e32 v84, v88
	v_rcp_f32_e32 v85, v89
	v_rcp_f32_e32 v86, v100
	v_rcp_f32_e32 v87, v101
	v_pk_mul_f32 v[82:83], v[82:83], v[90:91]
	v_pk_mul_f32 v[90:91], v[84:85], v[92:93]
	v_pk_mul_f32 v[84:85], v[82:83], v[82:83]
	v_add_f32_e32 v100, v107, v104
	v_rcp_f32_e32 v88, v102
	v_rcp_f32_e32 v89, v103
	v_add_f32_e32 v84, v84, v100
	v_pk_mul_f32 v[92:93], v[90:91], v[90:91]
	v_add_f32_e32 v84, v85, v84
	v_pk_mul_f32 v[86:87], v[86:87], v[94:95]
	v_add_f32_e32 v84, v92, v84
	v_pk_mul_f32 v[94:95], v[86:87], v[86:87]
	v_add_f32_e32 v84, v93, v84
	v_pk_mul_f32 v[88:89], v[88:89], v[96:97]
	v_add_f32_e32 v84, v94, v84
	v_pk_mul_f32 v[96:97], v[88:89], v[88:89]
	v_add_f32_e32 v84, v95, v84
	v_add_f32_e32 v84, v96, v84
	v_add_f32_e32 v85, v97, v84
	ds_bpermute_b32 v92, v122, v85
	v_cvt_pk_bf16_f32 v84, v82, v83
	v_cvt_pk_bf16_f32 v86, v86, v87
	v_cvt_pk_bf16_f32 v87, v88, v89
	s_waitcnt lgkmcnt(0)
	v_add_f32_e32 v82, v85, v92
	ds_bpermute_b32 v83, v116, v82
	v_cvt_pk_bf16_f32 v85, v90, v91
	global_store_dwordx4 v[114:115], v[84:87], off offset:1280
	s_and_saveexec_b64 s[22:23], s[4:5]
	s_cbranch_execz .LBB0_596
	s_add_u32 s26, s36, s92
	s_addc_u32 s27, s37, s93
	v_lshl_add_u64 v[84:85], v[98:99], 4, s[26:27]
	s_lshl_b32 s52, s38, 2
	v_lshl_add_u64 v[84:85], v[84:85], 0, s[52:53]
	s_waitcnt lgkmcnt(0)
	v_add_f32_e32 v82, v82, v83
	global_store_dword v[84:85], v82, off
; __device__ __forceinline__ unsigned cvt_pk_bf16(float lo, float hi) { const f32x2 v = {lo, hi}; return __builtin_bit_cast(unsigned, __builtin_convertvector(v, bf16x2_t)); }
; __device__ __forceinline__ float bf_lo(unsigned w) { return __uint_as_float(w << 16); }
; __device__ __forceinline__ float bf_hi(unsigned w) { return __uint_as_float(w & 0xffff0000u); }
; __device__ __forceinline__ float fast_sigmoid(float v) { return __builtin_amdgcn_rcpf(1.0f + __builtin_amdgcn_exp2f(-1.4426950408889634f * v)); }
; #define ssq2 ((float*)(WSPTR() + WS_SSQ2))
;     __device__ __forceinline__ void operator()(const f32x4 (&acc)[2][2][4][2], const Unit& u, int wr, int wc, int fr, int fq) const {
;     ...
;                 const int row = row0 + ai * HALF + m * 16;
;                 float ss = 0.f;
; #pragma unroll
;                 for (int bj = 0; bj < 2; ++bj) {
;                     const int c0 = u.pn * BM + bj * HALF + wc * 32 + 8 * fq;
;                     const u32x4 zw = *(const u32x4*)(z + (size_t)row * 512 + c0);
;                     const f32x4 b0 = *(const f32x4*)(bglu + c0), b1 = *(const f32x4*)(bglu + c0 + 4);
;                     const f32x4 a0 = acc[ai][bj][m][0] + b0, a1 = acc[ai][bj][m][1] + b1;
;                     float o[8];
;                     o[0] = bf_lo(zw.x) * fast_sigmoid(a0[0]); o[1] = bf_hi(zw.x) * fast_sigmoid(a0[1]);
;                     o[2] = bf_lo(zw.y) * fast_sigmoid(a0[2]); o[3] = bf_hi(zw.y) * fast_sigmoid(a0[3]);
;                     o[4] = bf_lo(zw.z) * fast_sigmoid(a1[0]); o[5] = bf_hi(zw.z) * fast_sigmoid(a1[1]);
;                     o[6] = bf_lo(zw.w) * fast_sigmoid(a1[2]); o[7] = bf_hi(zw.w) * fast_sigmoid(a1[3]);
; #pragma unroll
;                     for (int j = 0; j < 8; ++j) ss += o[j] * o[j];
;                     u32x4 w; w.x = cvt_pk_bf16(o[0], o[1]); w.y = cvt_pk_bf16(o[2], o[3]); w.z = cvt_pk_bf16(o[4], o[5]); w.w = cvt_pk_bf16(o[6], o[7]);
;                     *(u32x4*)(s + (size_t)row * 1024 + 512 + c0) = w;
;                 }
;                 ss += __shfl_xor(ss, 16); ss += __shfl_xor(ss, 32); if (fq == 0) ssq2[((size_t)u.pn * 32768 + row) * 4 + wc] = ss;
.LBB0_596:
	s_or_b64 exec, exec, s[22:23]
	s_waitcnt vmcnt(0)
	s_mov_b32 s100, 0x24000
	s_mov_b32 s101, 0
	v_lshl_add_u64 v[228:229], v[226:227], 0, s[100:101]
	global_load_dwordx4 v[230:233], v[228:229], off
	global_load_dwordx4 v[234:237], v[228:229], off offset:256
	s_nop 1
	v_or_b32_e32 v82, 48, v144
	s_waitcnt lgkmcnt(0)
	v_ashrrev_i32_e32 v83, 31, v82
	v_lshlrev_b64 v[92:93], 10, v[82:83]
	v_lshl_add_u64 v[92:93], s[76:77], 0, v[92:93]
	v_lshl_add_u64 v[96:97], v[92:93], 0, v[142:143]
	v_lshlrev_b64 v[98:99], 11, v[82:83]
	v_lshl_add_u64 v[98:99], s[78:79], 0, v[98:99]
	v_lshl_add_u64 v[98:99], v[98:99], 0, v[142:143]
	v_mov_b32_e32 v84, v184
	v_mov_b32_e32 v85, v185
	v_mov_b32_e32 v86, v186
	v_mov_b32_e32 v87, v187
	v_mov_b32_e32 v88, v188
	v_mov_b32_e32 v89, v189
	v_mov_b32_e32 v90, v190
	v_mov_b32_e32 v91, v191
	v_mov_b32_e32 v92, v200
	v_mov_b32_e32 v93, v201
	v_mov_b32_e32 v94, v202
	v_mov_b32_e32 v95, v203
	v_pk_add_f32 v[80:81], v[80:81], v[86:87]
	v_pk_add_f32 v[78:79], v[78:79], v[84:85]
	v_pk_add_f32 v[76:77], v[76:77], v[90:91]
	v_pk_add_f32 v[74:75], v[74:75], v[88:89]
	v_mul_f32_e32 v78, 0xbfb8aa3b, v78
	v_mul_f32_e32 v79, 0xbfb8aa3b, v79
	v_mul_f32_e32 v80, 0xbfb8aa3b, v80
	v_mul_f32_e32 v81, 0xbfb8aa3b, v81
	v_mul_f32_e32 v74, 0xbfb8aa3b, v74
	v_mul_f32_e32 v75, 0xbfb8aa3b, v75
	v_mul_f32_e32 v76, 0xbfb8aa3b, v76
	v_mul_f32_e32 v77, 0xbfb8aa3b, v77
	v_exp_f32_e32 v84, v78
	v_exp_f32_e32 v85, v79
	v_exp_f32_e32 v86, v80
	v_exp_f32_e32 v87, v81
	v_exp_f32_e32 v88, v74
	v_exp_f32_e32 v89, v75
	v_exp_f32_e32 v90, v76
	v_exp_f32_e32 v91, v77
	v_add_f32_e32 v84, 1.0, v84
	v_add_f32_e32 v85, 1.0, v85
	v_add_f32_e32 v86, 1.0, v86
	v_add_f32_e32 v87, 1.0, v87
	v_add_f32_e32 v88, 1.0, v88
	v_add_f32_e32 v89, 1.0, v89
	v_add_f32_e32 v90, 1.0, v90
	v_add_f32_e32 v91, 1.0, v91
	v_rcp_f32_e32 v84, v84
	v_rcp_f32_e32 v85, v85
	v_rcp_f32_e32 v86, v86
	v_rcp_f32_e32 v87, v87
	v_rcp_f32_e32 v88, v88
	v_rcp_f32_e32 v89, v89
	v_rcp_f32_e32 v90, v90
	v_rcp_f32_e32 v91, v91
	v_lshlrev_b32_e32 v74, 16, v92
	v_and_b32_e32 v75, 0xffff0000, v92
	v_lshlrev_b32_e32 v76, 16, v93
	v_and_b32_e32 v77, 0xffff0000, v93
	v_lshlrev_b32_e32 v78, 16, v94
	v_and_b32_e32 v79, 0xffff0000, v94
	v_lshlrev_b32_e32 v80, 16, v95
	v_and_b32_e32 v81, 0xffff0000, v95
	v_pk_mul_f32 v[92:93], v[84:85], v[74:75]
	v_pk_mul_f32 v[94:95], v[86:87], v[76:77]
	v_pk_mul_f32 v[88:89], v[88:89], v[78:79]
	v_pk_mul_f32 v[90:91], v[90:91], v[80:81]
	v_cvt_pk_bf16_f32 v74, v92, v93
	v_cvt_pk_bf16_f32 v75, v94, v95
	v_cvt_pk_bf16_f32 v76, v88, v89
	v_cvt_pk_bf16_f32 v77, v90, v91
	global_store_dwordx4 v[98:99], v[74:77], off offset:1024
	s_nop 0
	v_pk_mul_f32 v[92:93], v[92:93], v[92:93]
	v_pk_mul_f32 v[94:95], v[94:95], v[94:95]
	v_add_f32_e32 v92, v92, v93
	v_add_f32_e32 v92, v94, v92
	v_pk_mul_f32 v[88:89], v[88:89], v[88:89]
	v_add_f32_e32 v92, v95, v92
	v_add_f32_e32 v88, v88, v92
	v_pk_mul_f32 v[90:91], v[90:91], v[90:91]
	v_add_f32_e32 v88, v89, v88
	v_add_f32_e32 v88, v90, v88
	v_mov_b32_e32 v74, v192
	v_mov_b32_e32 v75, v193
	v_mov_b32_e32 v76, v194
	v_mov_b32_e32 v77, v195
	v_mov_b32_e32 v78, v196
	v_mov_b32_e32 v79, v197
	v_mov_b32_e32 v80, v198
	v_mov_b32_e32 v81, v199
	v_mov_b32_e32 v84, v204
	v_mov_b32_e32 v85, v205
	v_mov_b32_e32 v86, v206
	v_mov_b32_e32 v87, v207
	v_pk_add_f32 v[70:71], v[70:71], v[74:75]
	v_pk_add_f32 v[72:73], v[72:73], v[76:77]
	v_pk_add_f32 v[66:67], v[66:67], v[78:79]
	v_mul_f32_e32 v70, 0xbfb8aa3b, v70
	v_mul_f32_e32 v71, 0xbfb8aa3b, v71
	v_pk_add_f32 v[68:69], v[68:69], v[80:81]
	v_mul_f32_e32 v72, 0xbfb8aa3b, v72
	v_mul_f32_e32 v73, 0xbfb8aa3b, v73
	v_mul_f32_e32 v66, 0xbfb8aa3b, v66
	v_mul_f32_e32 v67, 0xbfb8aa3b, v67
	v_exp_f32_e32 v70, v70
	v_exp_f32_e32 v71, v71
	v_mul_f32_e32 v68, 0xbfb8aa3b, v68
	v_mul_f32_e32 v69, 0xbfb8aa3b, v69
	v_exp_f32_e32 v72, v72
	v_exp_f32_e32 v73, v73
	v_exp_f32_e32 v66, v66
	v_exp_f32_e32 v67, v67
	v_exp_f32_e32 v68, v68
	v_exp_f32_e32 v69, v69
	v_add_f32_e32 v70, 1.0, v70
	v_add_f32_e32 v71, 1.0, v71
	v_lshlrev_b32_e32 v74, 16, v84
	v_and_b32_e32 v75, 0xffff0000, v84
	v_lshlrev_b32_e32 v76, 16, v85
	v_and_b32_e32 v77, 0xffff0000, v85
	v_add_f32_e32 v72, 1.0, v72
	v_add_f32_e32 v73, 1.0, v73
	v_add_f32_e32 v84, 1.0, v66
	v_add_f32_e32 v85, 1.0, v67
	v_rcp_f32_e32 v66, v70
	v_rcp_f32_e32 v67, v71
	v_lshlrev_b32_e32 v78, 16, v86
	v_and_b32_e32 v79, 0xffff0000, v86
	v_lshlrev_b32_e32 v80, 16, v87
	v_and_b32_e32 v81, 0xffff0000, v87
	v_add_f32_e32 v86, 1.0, v68
	v_add_f32_e32 v87, 1.0, v69
	v_rcp_f32_e32 v68, v72
	v_rcp_f32_e32 v69, v73
	v_rcp_f32_e32 v70, v84
	v_rcp_f32_e32 v71, v85
	v_pk_mul_f32 v[66:67], v[66:67], v[74:75]
	v_pk_mul_f32 v[74:75], v[68:69], v[76:77]
	v_pk_mul_f32 v[68:69], v[66:67], v[66:67]
	v_add_f32_e32 v84, v91, v88
	v_rcp_f32_e32 v72, v86
	v_rcp_f32_e32 v73, v87
	v_add_f32_e32 v68, v68, v84
	v_pk_mul_f32 v[76:77], v[74:75], v[74:75]
	v_add_f32_e32 v68, v69, v68
	v_pk_mul_f32 v[70:71], v[70:71], v[78:79]
	v_add_f32_e32 v68, v76, v68
	v_pk_mul_f32 v[78:79], v[70:71], v[70:71]
	v_add_f32_e32 v68, v77, v68
	v_pk_mul_f32 v[72:73], v[72:73], v[80:81]
	v_add_f32_e32 v68, v78, v68
	v_pk_mul_f32 v[80:81], v[72:73], v[72:73]
	v_add_f32_e32 v68, v79, v68
	v_add_f32_e32 v68, v80, v68
	v_add_f32_e32 v69, v81, v68
	ds_bpermute_b32 v76, v122, v69
	v_cvt_pk_bf16_f32 v68, v66, v67
	v_cvt_pk_bf16_f32 v70, v70, v71
	v_cvt_pk_bf16_f32 v71, v72, v73
	s_waitcnt lgkmcnt(0)
	v_add_f32_e32 v66, v69, v76
	ds_bpermute_b32 v67, v116, v66
	v_cvt_pk_bf16_f32 v69, v74, v75
	global_store_dwordx4 v[98:99], v[68:71], off offset:1280
	s_and_saveexec_b64 s[22:23], s[4:5]
	s_cbranch_execz .LBB0_598
	s_add_u32 s26, s36, s92
	s_addc_u32 s27, s37, s93
	v_lshl_add_u64 v[68:69], v[82:83], 4, s[26:27]
	s_lshl_b32 s52, s38, 2
	v_lshl_add_u64 v[68:69], v[68:69], 0, s[52:53]
	s_waitcnt lgkmcnt(0)
	v_add_f32_e32 v66, v66, v67
	global_store_dword v[68:69], v66, off
; __device__ __forceinline__ unsigned cvt_pk_bf16(float lo, float hi) { const f32x2 v = {lo, hi}; return __builtin_bit_cast(unsigned, __builtin_convertvector(v, bf16x2_t)); }
; __device__ __forceinline__ float bf_lo(unsigned w) { return __uint_as_float(w << 16); }
; __device__ __forceinline__ float bf_hi(unsigned w) { return __uint_as_float(w & 0xffff0000u); }
; __device__ __forceinline__ float fast_sigmoid(float v) { return __builtin_amdgcn_rcpf(1.0f + __builtin_amdgcn_exp2f(-1.4426950408889634f * v)); }
; #define ssq2 ((float*)(WSPTR() + WS_SSQ2))
;     __device__ __forceinline__ void operator()(const f32x4 (&acc)[2][2][4][2], const Unit& u, int wr, int wc, int fr, int fq) const {
;     ...
;                 const int row = row0 + ai * HALF + m * 16;
;                 float ss = 0.f;
; #pragma unroll
;                 for (int bj = 0; bj < 2; ++bj) {
;                     const int c0 = u.pn * BM + bj * HALF + wc * 32 + 8 * fq;
;                     const u32x4 zw = *(const u32x4*)(z + (size_t)row * 512 + c0);
;                     const f32x4 b0 = *(const f32x4*)(bglu + c0), b1 = *(const f32x4*)(bglu + c0 + 4);
;                     const f32x4 a0 = acc[ai][bj][m][0] + b0, a1 = acc[ai][bj][m][1] + b1;
;                     float o[8];
;                     o[0] = bf_lo(zw.x) * fast_sigmoid(a0[0]); o[1] = bf_hi(zw.x) * fast_sigmoid(a0[1]);
;                     o[2] = bf_lo(zw.y) * fast_sigmoid(a0[2]); o[3] = bf_hi(zw.y) * fast_sigmoid(a0[3]);
;                     o[4] = bf_lo(zw.z) * fast_sigmoid(a1[0]); o[5] = bf_hi(zw.z) * fast_sigmoid(a1[1]);
;                     o[6] = bf_lo(zw.w) * fast_sigmoid(a1[2]); o[7] = bf_hi(zw.w) * fast_sigmoid(a1[3]);
; #pragma unroll
;                     for (int j = 0; j < 8; ++j) ss += o[j] * o[j];
;                     u32x4 w; w.x = cvt_pk_bf16(o[0], o[1]); w.y = cvt_pk_bf16(o[2], o[3]); w.z = cvt_pk_bf16(o[4], o[5]); w.w = cvt_pk_bf16(o[6], o[7]);
;                     *(u32x4*)(s + (size_t)row * 1024 + 512 + c0) = w;
;                 }
;                 ss += __shfl_xor(ss, 16); ss += __shfl_xor(ss, 32); if (fq == 0) ssq2[((size_t)u.pn * 32768 + row) * 4 + wc] = ss;
.LBB0_598:
	s_or_b64 exec, exec, s[22:23]
	s_waitcnt vmcnt(0)
	s_mov_b32 s100, 0x28000
	s_mov_b32 s101, 0
	v_lshl_add_u64 v[228:229], v[226:227], 0, s[100:101]
	global_load_dwordx4 v[200:203], v[228:229], off
	global_load_dwordx4 v[204:207], v[228:229], off offset:256
	s_nop 1
	v_add_u32_e32 v66, 0x80, v144
	s_waitcnt lgkmcnt(0)
	v_ashrrev_i32_e32 v67, 31, v66
	v_lshlrev_b64 v[76:77], 10, v[66:67]
	v_lshl_add_u64 v[76:77], s[76:77], 0, v[76:77]
	v_lshl_add_u64 v[80:81], v[76:77], 0, v[142:143]
	v_lshlrev_b64 v[82:83], 11, v[66:67]
	v_lshl_add_u64 v[82:83], s[78:79], 0, v[82:83]
	v_lshl_add_u64 v[82:83], v[82:83], 0, v[142:143]
	v_mov_b32_e32 v68, v184
	v_mov_b32_e32 v69, v185
	v_mov_b32_e32 v70, v186
	v_mov_b32_e32 v71, v187
	v_mov_b32_e32 v72, v188
	v_mov_b32_e32 v73, v189
	v_mov_b32_e32 v74, v190
	v_mov_b32_e32 v75, v191
	v_mov_b32_e32 v76, v210
	v_mov_b32_e32 v77, v211
	v_mov_b32_e32 v78, v212
	v_mov_b32_e32 v79, v213
	v_pk_add_f32 v[64:65], v[64:65], v[70:71]
	v_pk_add_f32 v[62:63], v[62:63], v[68:69]
	v_pk_add_f32 v[60:61], v[60:61], v[74:75]
	v_pk_add_f32 v[58:59], v[58:59], v[72:73]
	v_mul_f32_e32 v62, 0xbfb8aa3b, v62
	v_mul_f32_e32 v63, 0xbfb8aa3b, v63
	v_mul_f32_e32 v64, 0xbfb8aa3b, v64
	v_mul_f32_e32 v65, 0xbfb8aa3b, v65
	v_mul_f32_e32 v58, 0xbfb8aa3b, v58
	v_mul_f32_e32 v59, 0xbfb8aa3b, v59
	v_mul_f32_e32 v60, 0xbfb8aa3b, v60
	v_mul_f32_e32 v61, 0xbfb8aa3b, v61
	v_exp_f32_e32 v68, v62
	v_exp_f32_e32 v69, v63
	v_exp_f32_e32 v70, v64
	v_exp_f32_e32 v71, v65
	v_exp_f32_e32 v72, v58
	v_exp_f32_e32 v73, v59
	v_exp_f32_e32 v74, v60
	v_exp_f32_e32 v75, v61
	v_add_f32_e32 v68, 1.0, v68
	v_add_f32_e32 v69, 1.0, v69
	v_add_f32_e32 v70, 1.0, v70
	v_add_f32_e32 v71, 1.0, v71
	v_add_f32_e32 v72, 1.0, v72
	v_add_f32_e32 v73, 1.0, v73
	v_add_f32_e32 v74, 1.0, v74
	v_add_f32_e32 v75, 1.0, v75
	v_rcp_f32_e32 v68, v68
	v_rcp_f32_e32 v69, v69
	v_rcp_f32_e32 v70, v70
	v_rcp_f32_e32 v71, v71
	v_rcp_f32_e32 v72, v72
	v_rcp_f32_e32 v73, v73
	v_rcp_f32_e32 v74, v74
	v_rcp_f32_e32 v75, v75
	v_lshlrev_b32_e32 v58, 16, v76
	v_and_b32_e32 v59, 0xffff0000, v76
	v_lshlrev_b32_e32 v60, 16, v77
	v_and_b32_e32 v61, 0xffff0000, v77
	v_lshlrev_b32_e32 v62, 16, v78
	v_and_b32_e32 v63, 0xffff0000, v78
	v_lshlrev_b32_e32 v64, 16, v79
	v_and_b32_e32 v65, 0xffff0000, v79
	v_pk_mul_f32 v[76:77], v[68:69], v[58:59]
	v_pk_mul_f32 v[78:79], v[70:71], v[60:61]
	v_pk_mul_f32 v[72:73], v[72:73], v[62:63]
	v_pk_mul_f32 v[74:75], v[74:75], v[64:65]
	v_cvt_pk_bf16_f32 v58, v76, v77
	v_cvt_pk_bf16_f32 v59, v78, v79
	v_cvt_pk_bf16_f32 v60, v72, v73
	v_cvt_pk_bf16_f32 v61, v74, v75
	global_store_dwordx4 v[82:83], v[58:61], off offset:1024
	s_nop 0
	v_pk_mul_f32 v[76:77], v[76:77], v[76:77]
	v_pk_mul_f32 v[78:79], v[78:79], v[78:79]
	v_add_f32_e32 v76, v76, v77
	v_add_f32_e32 v76, v78, v76
	v_pk_mul_f32 v[72:73], v[72:73], v[72:73]
	v_add_f32_e32 v76, v79, v76
	v_add_f32_e32 v72, v72, v76
	v_pk_mul_f32 v[74:75], v[74:75], v[74:75]
	v_add_f32_e32 v72, v73, v72
	v_add_f32_e32 v72, v74, v72
	v_mov_b32_e32 v58, v192
	v_mov_b32_e32 v59, v193
	v_mov_b32_e32 v60, v194
	v_mov_b32_e32 v61, v195
	v_mov_b32_e32 v62, v196
	v_mov_b32_e32 v63, v197
	v_mov_b32_e32 v64, v198
	v_mov_b32_e32 v65, v199
	v_mov_b32_e32 v68, v214
	v_mov_b32_e32 v69, v215
	v_mov_b32_e32 v70, v216
	v_mov_b32_e32 v71, v217
	v_pk_add_f32 v[54:55], v[54:55], v[58:59]
	v_pk_add_f32 v[56:57], v[56:57], v[60:61]
	v_pk_add_f32 v[50:51], v[50:51], v[62:63]
	v_mul_f32_e32 v54, 0xbfb8aa3b, v54
	v_mul_f32_e32 v55, 0xbfb8aa3b, v55
	v_pk_add_f32 v[52:53], v[52:53], v[64:65]
	v_mul_f32_e32 v56, 0xbfb8aa3b, v56
	v_mul_f32_e32 v57, 0xbfb8aa3b, v57
	v_mul_f32_e32 v50, 0xbfb8aa3b, v50
	v_mul_f32_e32 v51, 0xbfb8aa3b, v51
	v_exp_f32_e32 v54, v54
	v_exp_f32_e32 v55, v55
	v_mul_f32_e32 v52, 0xbfb8aa3b, v52
	v_mul_f32_e32 v53, 0xbfb8aa3b, v53
	v_exp_f32_e32 v56, v56
	v_exp_f32_e32 v57, v57
	v_exp_f32_e32 v50, v50
	v_exp_f32_e32 v51, v51
	v_exp_f32_e32 v52, v52
	v_exp_f32_e32 v53, v53
	v_add_f32_e32 v54, 1.0, v54
	v_add_f32_e32 v55, 1.0, v55
	v_lshlrev_b32_e32 v58, 16, v68
	v_and_b32_e32 v59, 0xffff0000, v68
	v_lshlrev_b32_e32 v60, 16, v69
	v_and_b32_e32 v61, 0xffff0000, v69
	v_add_f32_e32 v56, 1.0, v56
	v_add_f32_e32 v57, 1.0, v57
	v_add_f32_e32 v68, 1.0, v50
	v_add_f32_e32 v69, 1.0, v51
	v_rcp_f32_e32 v50, v54
	v_rcp_f32_e32 v51, v55
	v_lshlrev_b32_e32 v62, 16, v70
	v_and_b32_e32 v63, 0xffff0000, v70
	v_lshlrev_b32_e32 v64, 16, v71
	v_and_b32_e32 v65, 0xffff0000, v71
	v_add_f32_e32 v70, 1.0, v52
	v_add_f32_e32 v71, 1.0, v53
	v_rcp_f32_e32 v52, v56
	v_rcp_f32_e32 v53, v57
	v_rcp_f32_e32 v54, v68
	v_rcp_f32_e32 v55, v69
	v_pk_mul_f32 v[50:51], v[50:51], v[58:59]
	v_pk_mul_f32 v[58:59], v[52:53], v[60:61]
	v_pk_mul_f32 v[52:53], v[50:51], v[50:51]
	v_add_f32_e32 v68, v75, v72
	v_rcp_f32_e32 v56, v70
	v_rcp_f32_e32 v57, v71
	v_add_f32_e32 v52, v52, v68
	v_pk_mul_f32 v[60:61], v[58:59], v[58:59]
	v_add_f32_e32 v52, v53, v52
	v_pk_mul_f32 v[54:55], v[54:55], v[62:63]
	v_add_f32_e32 v52, v60, v52
	v_pk_mul_f32 v[62:63], v[54:55], v[54:55]
	v_add_f32_e32 v52, v61, v52
	v_pk_mul_f32 v[56:57], v[56:57], v[64:65]
	v_add_f32_e32 v52, v62, v52
	v_pk_mul_f32 v[64:65], v[56:57], v[56:57]
	v_add_f32_e32 v52, v63, v52
	v_add_f32_e32 v52, v64, v52
	v_add_f32_e32 v53, v65, v52
	ds_bpermute_b32 v60, v122, v53
	v_cvt_pk_bf16_f32 v52, v50, v51
	v_cvt_pk_bf16_f32 v54, v54, v55
	v_cvt_pk_bf16_f32 v55, v56, v57
	s_waitcnt lgkmcnt(0)
	v_add_f32_e32 v50, v53, v60
	ds_bpermute_b32 v51, v116, v50
	v_cvt_pk_bf16_f32 v53, v58, v59
	global_store_dwordx4 v[82:83], v[52:55], off offset:1280
	s_and_saveexec_b64 s[22:23], s[4:5]
	s_cbranch_execz .LBB0_600
	s_add_u32 s26, s36, s92
	s_addc_u32 s27, s37, s93
	v_lshl_add_u64 v[52:53], v[66:67], 4, s[26:27]
	s_lshl_b32 s52, s38, 2
	v_lshl_add_u64 v[52:53], v[52:53], 0, s[52:53]
	s_waitcnt lgkmcnt(0)
	v_add_f32_e32 v50, v50, v51
	global_store_dword v[52:53], v50, off
; __device__ __forceinline__ unsigned cvt_pk_bf16(float lo, float hi) { const f32x2 v = {lo, hi}; return __builtin_bit_cast(unsigned, __builtin_convertvector(v, bf16x2_t)); }
; __device__ __forceinline__ float bf_lo(unsigned w) { return __uint_as_float(w << 16); }
; __device__ __forceinline__ float bf_hi(unsigned w) { return __uint_as_float(w & 0xffff0000u); }
; __device__ __forceinline__ float fast_sigmoid(float v) { return __builtin_amdgcn_rcpf(1.0f + __builtin_amdgcn_exp2f(-1.4426950408889634f * v)); }
; #define ssq2 ((float*)(WSPTR() + WS_SSQ2))
;     __device__ __forceinline__ void operator()(const f32x4 (&acc)[2][2][4][2], const Unit& u, int wr, int wc, int fr, int fq) const {
;     ...
;                 const int row = row0 + ai * HALF + m * 16;
;                 float ss = 0.f;
; #pragma unroll
;                 for (int bj = 0; bj < 2; ++bj) {
;                     const int c0 = u.pn * BM + bj * HALF + wc * 32 + 8 * fq;
;                     const u32x4 zw = *(const u32x4*)(z + (size_t)row * 512 + c0);
;                     const f32x4 b0 = *(const f32x4*)(bglu + c0), b1 = *(const f32x4*)(bglu + c0 + 4);
;                     const f32x4 a0 = acc[ai][bj][m][0] + b0, a1 = acc[ai][bj][m][1] + b1;
;                     float o[8];
;                     o[0] = bf_lo(zw.x) * fast_sigmoid(a0[0]); o[1] = bf_hi(zw.x) * fast_sigmoid(a0[1]);
;                     o[2] = bf_lo(zw.y) * fast_sigmoid(a0[2]); o[3] = bf_hi(zw.y) * fast_sigmoid(a0[3]);
;                     o[4] = bf_lo(zw.z) * fast_sigmoid(a1[0]); o[5] = bf_hi(zw.z) * fast_sigmoid(a1[1]);
;                     o[6] = bf_lo(zw.w) * fast_sigmoid(a1[2]); o[7] = bf_hi(zw.w) * fast_sigmoid(a1[3]);
; #pragma unroll
;                     for (int j = 0; j < 8; ++j) ss += o[j] * o[j];
;                     u32x4 w; w.x = cvt_pk_bf16(o[0], o[1]); w.y = cvt_pk_bf16(o[2], o[3]); w.z = cvt_pk_bf16(o[4], o[5]); w.w = cvt_pk_bf16(o[6], o[7]);
;                     *(u32x4*)(s + (size_t)row * 1024 + 512 + c0) = w;
;                 }
;                 ss += __shfl_xor(ss, 16); ss += __shfl_xor(ss, 32); if (fq == 0) ssq2[((size_t)u.pn * 32768 + row) * 4 + wc] = ss;
.LBB0_600:
	s_or_b64 exec, exec, s[22:23]
	s_waitcnt vmcnt(0)
	s_mov_b32 s100, 0x2c000
	s_mov_b32 s101, 0
	v_lshl_add_u64 v[228:229], v[226:227], 0, s[100:101]
	global_load_dwordx4 v[210:213], v[228:229], off
	global_load_dwordx4 v[214:217], v[228:229], off offset:256
	s_nop 1
	v_add_u32_e32 v50, 0x90, v144
	s_waitcnt lgkmcnt(0)
	v_ashrrev_i32_e32 v51, 31, v50
	v_lshlrev_b64 v[60:61], 10, v[50:51]
	v_lshl_add_u64 v[60:61], s[76:77], 0, v[60:61]
	v_lshl_add_u64 v[64:65], v[60:61], 0, v[142:143]
	v_lshlrev_b64 v[66:67], 11, v[50:51]
	v_lshl_add_u64 v[66:67], s[78:79], 0, v[66:67]
	v_lshl_add_u64 v[66:67], v[66:67], 0, v[142:143]
	v_mov_b32_e32 v52, v184
	v_mov_b32_e32 v53, v185
	v_mov_b32_e32 v54, v186
	v_mov_b32_e32 v55, v187
	v_mov_b32_e32 v56, v188
	v_mov_b32_e32 v57, v189
	v_mov_b32_e32 v58, v190
	v_mov_b32_e32 v59, v191
	v_mov_b32_e32 v60, v230
	v_mov_b32_e32 v61, v231
	v_mov_b32_e32 v62, v232
	v_mov_b32_e32 v63, v233
	v_pk_add_f32 v[48:49], v[48:49], v[54:55]
	v_pk_add_f32 v[46:47], v[46:47], v[52:53]
	v_pk_add_f32 v[44:45], v[44:45], v[58:59]
	v_pk_add_f32 v[42:43], v[42:43], v[56:57]
	v_mul_f32_e32 v46, 0xbfb8aa3b, v46
	v_mul_f32_e32 v47, 0xbfb8aa3b, v47
	v_mul_f32_e32 v48, 0xbfb8aa3b, v48
	v_mul_f32_e32 v49, 0xbfb8aa3b, v49
	v_mul_f32_e32 v42, 0xbfb8aa3b, v42
	v_mul_f32_e32 v43, 0xbfb8aa3b, v43
	v_mul_f32_e32 v44, 0xbfb8aa3b, v44
	v_mul_f32_e32 v45, 0xbfb8aa3b, v45
	v_exp_f32_e32 v52, v46
	v_exp_f32_e32 v53, v47
	v_exp_f32_e32 v54, v48
	v_exp_f32_e32 v55, v49
	v_exp_f32_e32 v56, v42
	v_exp_f32_e32 v57, v43
	v_exp_f32_e32 v58, v44
	v_exp_f32_e32 v59, v45
	v_add_f32_e32 v52, 1.0, v52
	v_add_f32_e32 v53, 1.0, v53
	v_add_f32_e32 v54, 1.0, v54
	v_add_f32_e32 v55, 1.0, v55
	v_add_f32_e32 v56, 1.0, v56
	v_add_f32_e32 v57, 1.0, v57
	v_add_f32_e32 v58, 1.0, v58
	v_add_f32_e32 v59, 1.0, v59
	v_rcp_f32_e32 v52, v52
	v_rcp_f32_e32 v53, v53
	v_rcp_f32_e32 v54, v54
	v_rcp_f32_e32 v55, v55
	v_rcp_f32_e32 v56, v56
	v_rcp_f32_e32 v57, v57
	v_rcp_f32_e32 v58, v58
	v_rcp_f32_e32 v59, v59
	v_lshlrev_b32_e32 v42, 16, v60
	v_and_b32_e32 v43, 0xffff0000, v60
	v_lshlrev_b32_e32 v44, 16, v61
	v_and_b32_e32 v45, 0xffff0000, v61
	v_lshlrev_b32_e32 v46, 16, v62
	v_and_b32_e32 v47, 0xffff0000, v62
	v_lshlrev_b32_e32 v48, 16, v63
	v_and_b32_e32 v49, 0xffff0000, v63
	v_pk_mul_f32 v[60:61], v[52:53], v[42:43]
	v_pk_mul_f32 v[62:63], v[54:55], v[44:45]
	v_pk_mul_f32 v[56:57], v[56:57], v[46:47]
	v_pk_mul_f32 v[58:59], v[58:59], v[48:49]
	v_cvt_pk_bf16_f32 v42, v60, v61
	v_cvt_pk_bf16_f32 v43, v62, v63
	v_cvt_pk_bf16_f32 v44, v56, v57
	v_cvt_pk_bf16_f32 v45, v58, v59
	global_store_dwordx4 v[66:67], v[42:45], off offset:1024
	s_nop 0
	v_pk_mul_f32 v[60:61], v[60:61], v[60:61]
	v_pk_mul_f32 v[62:63], v[62:63], v[62:63]
	v_add_f32_e32 v60, v60, v61
	v_add_f32_e32 v60, v62, v60
	v_pk_mul_f32 v[56:57], v[56:57], v[56:57]
	v_add_f32_e32 v60, v63, v60
	v_add_f32_e32 v56, v56, v60
	v_pk_mul_f32 v[58:59], v[58:59], v[58:59]
	v_add_f32_e32 v56, v57, v56
	v_add_f32_e32 v56, v58, v56
	v_mov_b32_e32 v42, v192
	v_mov_b32_e32 v43, v193
	v_mov_b32_e32 v44, v194
	v_mov_b32_e32 v45, v195
	v_mov_b32_e32 v46, v196
	v_mov_b32_e32 v47, v197
	v_mov_b32_e32 v48, v198
	v_mov_b32_e32 v49, v199
	v_mov_b32_e32 v52, v234
	v_mov_b32_e32 v53, v235
	v_mov_b32_e32 v54, v236
	v_mov_b32_e32 v55, v237
	v_pk_add_f32 v[38:39], v[38:39], v[42:43]
	v_pk_add_f32 v[40:41], v[40:41], v[44:45]
	v_pk_add_f32 v[34:35], v[34:35], v[46:47]
	v_mul_f32_e32 v38, 0xbfb8aa3b, v38
	v_mul_f32_e32 v39, 0xbfb8aa3b, v39
	v_pk_add_f32 v[36:37], v[36:37], v[48:49]
	v_mul_f32_e32 v40, 0xbfb8aa3b, v40
	v_mul_f32_e32 v41, 0xbfb8aa3b, v41
	v_mul_f32_e32 v34, 0xbfb8aa3b, v34
	v_mul_f32_e32 v35, 0xbfb8aa3b, v35
	v_exp_f32_e32 v38, v38
	v_exp_f32_e32 v39, v39
	v_mul_f32_e32 v36, 0xbfb8aa3b, v36
	v_mul_f32_e32 v37, 0xbfb8aa3b, v37
	v_exp_f32_e32 v40, v40
	v_exp_f32_e32 v41, v41
	v_exp_f32_e32 v34, v34
	v_exp_f32_e32 v35, v35
	v_exp_f32_e32 v36, v36
	v_exp_f32_e32 v37, v37
	v_add_f32_e32 v38, 1.0, v38
	v_add_f32_e32 v39, 1.0, v39
	v_lshlrev_b32_e32 v42, 16, v52
	v_and_b32_e32 v43, 0xffff0000, v52
	v_lshlrev_b32_e32 v44, 16, v53
	v_and_b32_e32 v45, 0xffff0000, v53
	v_add_f32_e32 v40, 1.0, v40
	v_add_f32_e32 v41, 1.0, v41
	v_add_f32_e32 v52, 1.0, v34
	v_add_f32_e32 v53, 1.0, v35
	v_rcp_f32_e32 v34, v38
	v_rcp_f32_e32 v35, v39
	v_lshlrev_b32_e32 v46, 16, v54
	v_and_b32_e32 v47, 0xffff0000, v54
	v_lshlrev_b32_e32 v48, 16, v55
	v_and_b32_e32 v49, 0xffff0000, v55
	v_add_f32_e32 v54, 1.0, v36
	v_add_f32_e32 v55, 1.0, v37
	v_rcp_f32_e32 v36, v40
	v_rcp_f32_e32 v37, v41
	v_rcp_f32_e32 v38, v52
	v_rcp_f32_e32 v39, v53
	v_pk_mul_f32 v[34:35], v[34:35], v[42:43]
	v_pk_mul_f32 v[42:43], v[36:37], v[44:45]
	v_pk_mul_f32 v[36:37], v[34:35], v[34:35]
	v_add_f32_e32 v52, v59, v56
	v_rcp_f32_e32 v40, v54
	v_rcp_f32_e32 v41, v55
	v_add_f32_e32 v36, v36, v52
	v_pk_mul_f32 v[44:45], v[42:43], v[42:43]
	v_add_f32_e32 v36, v37, v36
	v_pk_mul_f32 v[38:39], v[38:39], v[46:47]
	v_add_f32_e32 v36, v44, v36
	v_pk_mul_f32 v[46:47], v[38:39], v[38:39]
	v_add_f32_e32 v36, v45, v36
	v_pk_mul_f32 v[40:41], v[40:41], v[48:49]
	v_add_f32_e32 v36, v46, v36
	v_pk_mul_f32 v[48:49], v[40:41], v[40:41]
	v_add_f32_e32 v36, v47, v36
	v_add_f32_e32 v36, v48, v36
	v_add_f32_e32 v37, v49, v36
	ds_bpermute_b32 v44, v122, v37
	v_cvt_pk_bf16_f32 v36, v34, v35
	v_cvt_pk_bf16_f32 v38, v38, v39
	v_cvt_pk_bf16_f32 v39, v40, v41
	s_waitcnt lgkmcnt(0)
	v_add_f32_e32 v34, v37, v44
	ds_bpermute_b32 v35, v116, v34
	v_cvt_pk_bf16_f32 v37, v42, v43
	global_store_dwordx4 v[66:67], v[36:39], off offset:1280
	s_and_saveexec_b64 s[22:23], s[4:5]
	s_cbranch_execz .LBB0_602
	s_add_u32 s26, s36, s92
	s_addc_u32 s27, s37, s93
	v_lshl_add_u64 v[36:37], v[50:51], 4, s[26:27]
	s_lshl_b32 s52, s38, 2
	v_lshl_add_u64 v[36:37], v[36:37], 0, s[52:53]
	s_waitcnt lgkmcnt(0)
	v_add_f32_e32 v34, v34, v35
	global_store_dword v[36:37], v34, off
; __device__ __forceinline__ unsigned cvt_pk_bf16(float lo, float hi) { const f32x2 v = {lo, hi}; return __builtin_bit_cast(unsigned, __builtin_convertvector(v, bf16x2_t)); }
; __device__ __forceinline__ float bf_lo(unsigned w) { return __uint_as_float(w << 16); }
; __device__ __forceinline__ float bf_hi(unsigned w) { return __uint_as_float(w & 0xffff0000u); }
; __device__ __forceinline__ float fast_sigmoid(float v) { return __builtin_amdgcn_rcpf(1.0f + __builtin_amdgcn_exp2f(-1.4426950408889634f * v)); }
; #define ssq2 ((float*)(WSPTR() + WS_SSQ2))
;     __device__ __forceinline__ void operator()(const f32x4 (&acc)[2][2][4][2], const Unit& u, int wr, int wc, int fr, int fq) const {
;     ...
;                 const int row = row0 + ai * HALF + m * 16;
;                 float ss = 0.f;
; #pragma unroll
;                 for (int bj = 0; bj < 2; ++bj) {
;                     const int c0 = u.pn * BM + bj * HALF + wc * 32 + 8 * fq;
;                     const u32x4 zw = *(const u32x4*)(z + (size_t)row * 512 + c0);
;                     const f32x4 b0 = *(const f32x4*)(bglu + c0), b1 = *(const f32x4*)(bglu + c0 + 4);
;                     const f32x4 a0 = acc[ai][bj][m][0] + b0, a1 = acc[ai][bj][m][1] + b1;
;                     float o[8];
;                     o[0] = bf_lo(zw.x) * fast_sigmoid(a0[0]); o[1] = bf_hi(zw.x) * fast_sigmoid(a0[1]);
;                     o[2] = bf_lo(zw.y) * fast_sigmoid(a0[2]); o[3] = bf_hi(zw.y) * fast_sigmoid(a0[3]);
;                     o[4] = bf_lo(zw.z) * fast_sigmoid(a1[0]); o[5] = bf_hi(zw.z) * fast_sigmoid(a1[1]);
;                     o[6] = bf_lo(zw.w) * fast_sigmoid(a1[2]); o[7] = bf_hi(zw.w) * fast_sigmoid(a1[3]);
; #pragma unroll
;                     for (int j = 0; j < 8; ++j) ss += o[j] * o[j];
;                     u32x4 w; w.x = cvt_pk_bf16(o[0], o[1]); w.y = cvt_pk_bf16(o[2], o[3]); w.z = cvt_pk_bf16(o[4], o[5]); w.w = cvt_pk_bf16(o[6], o[7]);
;                     *(u32x4*)(s + (size_t)row * 1024 + 512 + c0) = w;
;                 }
;                 ss += __shfl_xor(ss, 16); ss += __shfl_xor(ss, 32); if (fq == 0) ssq2[((size_t)u.pn * 32768 + row) * 4 + wc] = ss;
.LBB0_602:
	s_or_b64 exec, exec, s[22:23]
	s_waitcnt vmcnt(0)
	v_add_u32_e32 v34, 0xa0, v144
	s_waitcnt lgkmcnt(0)
	v_ashrrev_i32_e32 v35, 31, v34
	v_lshlrev_b64 v[44:45], 10, v[34:35]
	v_lshl_add_u64 v[44:45], s[76:77], 0, v[44:45]
	v_lshl_add_u64 v[48:49], v[44:45], 0, v[142:143]
	v_lshlrev_b64 v[50:51], 11, v[34:35]
	v_lshl_add_u64 v[50:51], s[78:79], 0, v[50:51]
	v_lshl_add_u64 v[50:51], v[50:51], 0, v[142:143]
	v_mov_b32_e32 v36, v184
	v_mov_b32_e32 v37, v185
	v_mov_b32_e32 v38, v186
	v_mov_b32_e32 v39, v187
	v_mov_b32_e32 v40, v188
	v_mov_b32_e32 v41, v189
	v_mov_b32_e32 v42, v190
	v_mov_b32_e32 v43, v191
	v_mov_b32_e32 v44, v200
	v_mov_b32_e32 v45, v201
	v_mov_b32_e32 v46, v202
	v_mov_b32_e32 v47, v203
	v_pk_add_f32 v[32:33], v[32:33], v[38:39]
	v_pk_add_f32 v[30:31], v[30:31], v[36:37]
	v_pk_add_f32 v[28:29], v[28:29], v[42:43]
	v_pk_add_f32 v[26:27], v[26:27], v[40:41]
	v_mul_f32_e32 v30, 0xbfb8aa3b, v30
	v_mul_f32_e32 v31, 0xbfb8aa3b, v31
	v_mul_f32_e32 v32, 0xbfb8aa3b, v32
	v_mul_f32_e32 v33, 0xbfb8aa3b, v33
	v_mul_f32_e32 v26, 0xbfb8aa3b, v26
	v_mul_f32_e32 v27, 0xbfb8aa3b, v27
	v_mul_f32_e32 v28, 0xbfb8aa3b, v28
	v_mul_f32_e32 v29, 0xbfb8aa3b, v29
	v_exp_f32_e32 v36, v30
	v_exp_f32_e32 v37, v31
	v_exp_f32_e32 v38, v32
	v_exp_f32_e32 v39, v33
	v_exp_f32_e32 v40, v26
	v_exp_f32_e32 v41, v27
	v_exp_f32_e32 v42, v28
	v_exp_f32_e32 v43, v29
	v_add_f32_e32 v36, 1.0, v36
	v_add_f32_e32 v37, 1.0, v37
	v_add_f32_e32 v38, 1.0, v38
	v_add_f32_e32 v39, 1.0, v39
	v_add_f32_e32 v40, 1.0, v40
	v_add_f32_e32 v41, 1.0, v41
	v_add_f32_e32 v42, 1.0, v42
	v_add_f32_e32 v43, 1.0, v43
	v_rcp_f32_e32 v36, v36
	v_rcp_f32_e32 v37, v37
	v_rcp_f32_e32 v38, v38
	v_rcp_f32_e32 v39, v39
	v_rcp_f32_e32 v40, v40
	v_rcp_f32_e32 v41, v41
	v_rcp_f32_e32 v42, v42
	v_rcp_f32_e32 v43, v43
	v_lshlrev_b32_e32 v26, 16, v44
	v_and_b32_e32 v27, 0xffff0000, v44
	v_lshlrev_b32_e32 v28, 16, v45
	v_and_b32_e32 v29, 0xffff0000, v45
	v_lshlrev_b32_e32 v30, 16, v46
	v_and_b32_e32 v31, 0xffff0000, v46
	v_lshlrev_b32_e32 v32, 16, v47
	v_and_b32_e32 v33, 0xffff0000, v47
	v_pk_mul_f32 v[44:45], v[36:37], v[26:27]
	v_pk_mul_f32 v[46:47], v[38:39], v[28:29]
	v_pk_mul_f32 v[40:41], v[40:41], v[30:31]
	v_pk_mul_f32 v[42:43], v[42:43], v[32:33]
	v_cvt_pk_bf16_f32 v26, v44, v45
	v_cvt_pk_bf16_f32 v27, v46, v47
	v_cvt_pk_bf16_f32 v28, v40, v41
	v_cvt_pk_bf16_f32 v29, v42, v43
	global_store_dwordx4 v[50:51], v[26:29], off offset:1024
	s_nop 0
	v_pk_mul_f32 v[44:45], v[44:45], v[44:45]
	v_pk_mul_f32 v[46:47], v[46:47], v[46:47]
	v_add_f32_e32 v44, v44, v45
	v_add_f32_e32 v44, v46, v44
	v_pk_mul_f32 v[40:41], v[40:41], v[40:41]
	v_add_f32_e32 v44, v47, v44
	v_add_f32_e32 v40, v40, v44
	v_pk_mul_f32 v[42:43], v[42:43], v[42:43]
	v_add_f32_e32 v40, v41, v40
	v_add_f32_e32 v40, v42, v40
	v_mov_b32_e32 v26, v192
	v_mov_b32_e32 v27, v193
	v_mov_b32_e32 v28, v194
	v_mov_b32_e32 v29, v195
	v_mov_b32_e32 v30, v196
	v_mov_b32_e32 v31, v197
	v_mov_b32_e32 v32, v198
	v_mov_b32_e32 v33, v199
	v_mov_b32_e32 v36, v204
	v_mov_b32_e32 v37, v205
	v_mov_b32_e32 v38, v206
	v_mov_b32_e32 v39, v207
	v_pk_add_f32 v[22:23], v[22:23], v[26:27]
	v_pk_add_f32 v[24:25], v[24:25], v[28:29]
	v_pk_add_f32 v[18:19], v[18:19], v[30:31]
	v_mul_f32_e32 v22, 0xbfb8aa3b, v22
	v_mul_f32_e32 v23, 0xbfb8aa3b, v23
	v_pk_add_f32 v[20:21], v[20:21], v[32:33]
	v_mul_f32_e32 v24, 0xbfb8aa3b, v24
	v_mul_f32_e32 v25, 0xbfb8aa3b, v25
	v_mul_f32_e32 v18, 0xbfb8aa3b, v18
	v_mul_f32_e32 v19, 0xbfb8aa3b, v19
	v_exp_f32_e32 v22, v22
	v_exp_f32_e32 v23, v23
	v_mul_f32_e32 v20, 0xbfb8aa3b, v20
	v_mul_f32_e32 v21, 0xbfb8aa3b, v21
	v_exp_f32_e32 v24, v24
	v_exp_f32_e32 v25, v25
	v_exp_f32_e32 v18, v18
	v_exp_f32_e32 v19, v19
	v_exp_f32_e32 v20, v20
	v_exp_f32_e32 v21, v21
	v_add_f32_e32 v22, 1.0, v22
	v_add_f32_e32 v23, 1.0, v23
	v_lshlrev_b32_e32 v26, 16, v36
	v_and_b32_e32 v27, 0xffff0000, v36
	v_lshlrev_b32_e32 v28, 16, v37
	v_and_b32_e32 v29, 0xffff0000, v37
	v_add_f32_e32 v24, 1.0, v24
	v_add_f32_e32 v25, 1.0, v25
	v_add_f32_e32 v36, 1.0, v18
	v_add_f32_e32 v37, 1.0, v19
	v_rcp_f32_e32 v18, v22
	v_rcp_f32_e32 v19, v23
	v_lshlrev_b32_e32 v30, 16, v38
	v_and_b32_e32 v31, 0xffff0000, v38
	v_lshlrev_b32_e32 v32, 16, v39
	v_and_b32_e32 v33, 0xffff0000, v39
	v_add_f32_e32 v38, 1.0, v20
	v_add_f32_e32 v39, 1.0, v21
	v_rcp_f32_e32 v20, v24
	v_rcp_f32_e32 v21, v25
	v_rcp_f32_e32 v22, v36
	v_rcp_f32_e32 v23, v37
	v_pk_mul_f32 v[18:19], v[18:19], v[26:27]
	v_pk_mul_f32 v[26:27], v[20:21], v[28:29]
	v_pk_mul_f32 v[20:21], v[18:19], v[18:19]
	v_add_f32_e32 v36, v43, v40
	v_rcp_f32_e32 v24, v38
	v_rcp_f32_e32 v25, v39
	v_add_f32_e32 v20, v20, v36
	v_pk_mul_f32 v[28:29], v[26:27], v[26:27]
	v_add_f32_e32 v20, v21, v20
	v_pk_mul_f32 v[22:23], v[22:23], v[30:31]
	v_add_f32_e32 v20, v28, v20
	v_pk_mul_f32 v[30:31], v[22:23], v[22:23]
	v_add_f32_e32 v20, v29, v20
	v_pk_mul_f32 v[24:25], v[24:25], v[32:33]
	v_add_f32_e32 v20, v30, v20
	v_pk_mul_f32 v[32:33], v[24:25], v[24:25]
	v_add_f32_e32 v20, v31, v20
	v_add_f32_e32 v20, v32, v20
	v_add_f32_e32 v21, v33, v20
	ds_bpermute_b32 v28, v122, v21
	v_cvt_pk_bf16_f32 v20, v18, v19
	v_cvt_pk_bf16_f32 v22, v22, v23
	v_cvt_pk_bf16_f32 v23, v24, v25
	s_waitcnt lgkmcnt(0)
	v_add_f32_e32 v18, v21, v28
	ds_bpermute_b32 v19, v116, v18
	v_cvt_pk_bf16_f32 v21, v26, v27
	global_store_dwordx4 v[50:51], v[20:23], off offset:1280
	s_and_saveexec_b64 s[22:23], s[4:5]
	s_cbranch_execz .LBB0_604
	s_add_u32 s26, s36, s92
	s_addc_u32 s27, s37, s93
	v_lshl_add_u64 v[20:21], v[34:35], 4, s[26:27]
	s_lshl_b32 s52, s38, 2
	v_lshl_add_u64 v[20:21], v[20:21], 0, s[52:53]
	s_waitcnt lgkmcnt(0)
	v_add_f32_e32 v18, v18, v19
	global_store_dword v[20:21], v18, off
